# DSA half-row max exchanges via v_permlane32_swap instead of ds_bpermute
# baseline (speedup 1.0000x reference)
; #define LAS __attribute__((address_space(3)))
; #define MFMA32(a, b, c) __builtin_amdgcn_mfma_f32_32x32x16_bf16((a), (b), (c), 0, 0, 0)
; DI float fexp2(float x) { return __builtin_amdgcn_exp2f(x); }
; DI float half_max(float v) { return fmaxf(v, __shfl_xor(v, 32)); }
; DI void flash_qk_bias(const LAS unsigned char* kb, const bf16x8 (&qf)[4], f32x16& p0, f32x16& p1, int r32, int h, const bf16x8& m0, const bf16x8& m1, const bf16x8& ef) {
;     p0 = MFMA32(m0, ef, f16zero()); p1 = MFMA32(m1, ef, f16zero());
;     const int sw = (r32 >> 1) & 7;
; #pragma unroll
;     for (int s = 0; s < 4; ++s) {
;         const int off = r32 * 128 + (((2 * s + h) ^ sw) << 4);
;         const bf16x8 a0 = *(const LAS bf16x8*)(kb + off), a1 = *(const LAS bf16x8*)(kb + off + 4096);
;         p0 = MFMA32(a0, qf[s], p0); p1 = MFMA32(a1, qf[s], p1);
;     }
; DI void flash_pv2(FState& sa, FState& sb, f32x16& a0, f32x16& a1, bool rona, f32x16& b0, f32x16& b1, bool ronb, const LAS unsigned char* va, const LAS unsigned char* vbb, int lane) {
;     float mxa = fmaxf(a0[0], a1[0]), mxb = fmaxf(b0[0], b1[0]);
; #pragma unroll
;     for (int r = 1; r < 16; ++r) { asm("v_max3_f32 %0, %1, %2, %3" : "=v"(mxa) : "v"(mxa), "v"(a0[r]), "v"(a1[r])); asm("v_max3_f32 %0, %1, %2, %3" : "=v"(mxb) : "v"(mxb), "v"(b0[r]), "v"(b1[r])); }
;     mxa = half_max(mxa); mxb = half_max(mxb);
;     mxa = rona ? mxa : NINF; mxb = ronb ? mxb : NINF;
;     const bool upa = mxa > sa.m + THR_RAW, upb = mxb > sb.m + THR_RAW;
;     if (__any(upa || upb)) {
;         const float mna = upa ? mxa : sa.m, mnb = upb ? mxb : sb.m;
;         const float ala = upa ? fexp2((sa.m - mna) * SM_C) : 1.0f, alb = upb ? fexp2((sb.m - mnb) * SM_C) : 1.0f;
;         sa.m = mna; sa.l *= ala; sb.m = mnb; sb.l *= alb;
; #pragma unroll
;         for (int r = 0; r < 16; ++r) { sa.o0[r] *= ala; sa.o1[r] *= ala; sb.o0[r] *= alb; sb.o1[r] *= alb; }
;     }
.LBB0_726:
	s_or_b64 exec, exec, s[4:5]
	v_mov_b32_e32 v94, v90
	v_mov_b32_e32 v95, v90
	v_mov_b32_e32 v91, v90
	s_add_i32 s4, s16, 0xffff8000
	v_mov_b32_e32 v86, v90
	v_mov_b32_e32 v87, v90
	s_and_b32 s4, s4, 0x8000
	s_add_i32 s73, s4, 0
	v_mfma_f32_32x32x16_bf16 v[100:115], v[92:95], v[84:87], 0
	v_add_u32_e32 v99, s73, v201
	v_add_u32_e32 v179, v99, v165
	v_add_u32_e32 v187, v99, v216
	v_add_u32_e32 v192, v99, v217
	v_add_u32_e32 v193, v99, v218
	v_mov_b32_e32 v118, v98
	v_mov_b32_e32 v119, v98
	v_mfma_f32_32x32x16_bf16 v[68:83], v[88:91], v[84:87], 0
	ds_read_b128 v[88:91], v179
	ds_read_b128 v[92:95], v179 offset:4096
	v_mov_b32_e32 v99, v98
	s_cmp_lt_u32 s51, s71
	s_cselect_b64 s[4:5], -1, 0
	s_waitcnt lgkmcnt(0)
	v_mfma_f32_32x32x16_bf16 v[100:115], v[88:91], v[132:135], v[100:115]
	v_mfma_f32_32x32x16_bf16 v[68:83], v[92:95], v[132:135], v[68:83]
	ds_read_b128 v[88:91], v187
	ds_read_b128 v[92:95], v187 offset:4096
	s_waitcnt lgkmcnt(0)
	v_mfma_f32_32x32x16_bf16 v[100:115], v[88:91], v[136:139], v[100:115]
	v_mfma_f32_32x32x16_bf16 v[68:83], v[92:95], v[136:139], v[68:83]
	ds_read_b128 v[88:91], v192
	ds_read_b128 v[92:95], v192 offset:4096
	s_waitcnt lgkmcnt(0)
	v_mfma_f32_32x32x16_bf16 v[100:115], v[88:91], v[140:143], v[100:115]
	v_mfma_f32_32x32x16_bf16 v[68:83], v[92:95], v[140:143], v[68:83]
	ds_read_b128 v[88:91], v193
	ds_read_b128 v[92:95], v193 offset:4096
	ds_read_b128 v[182:185], v179 offset:16384
	ds_read_b128 v[188:191], v179 offset:20480
	v_mfma_f32_32x32x16_bf16 v[116:131], v[116:119], v[84:87], 0
	s_waitcnt lgkmcnt(0)
	v_mfma_f32_32x32x16_bf16 v[100:115], v[88:91], v[144:147], v[100:115]
	v_mfma_f32_32x32x16_bf16 v[68:83], v[92:95], v[144:147], v[68:83]
	v_mfma_f32_32x32x16_bf16 v[84:99], v[96:99], v[84:87], 0
	s_nop 10
	v_max_f32_e32 v179, v68, v68
	v_mfma_f32_32x32x16_bf16 v[116:131], v[182:185], v[132:135], v[116:131]
	v_mfma_f32_32x32x16_bf16 v[84:99], v[188:191], v[132:135], v[84:99]
	ds_read_b128 v[182:185], v187 offset:16384
	ds_read_b128 v[188:191], v187 offset:20480
	v_max_f32_e32 v187, v100, v100
	v_max_f32_e32 v179, v187, v179
	v_max3_f32 v179, v179, v101, v69
	v_max3_f32 v179, v179, v102, v70
	s_waitcnt lgkmcnt(0)
	v_mfma_f32_32x32x16_bf16 v[116:131], v[182:185], v[136:139], v[116:131]
	v_max3_f32 v179, v179, v103, v71
	v_max3_f32 v179, v179, v104, v72
	v_max3_f32 v179, v179, v105, v73
	v_max3_f32 v179, v179, v106, v74
	v_mfma_f32_32x32x16_bf16 v[84:99], v[188:191], v[136:139], v[84:99]
	ds_read_b128 v[182:185], v192 offset:16384
	ds_read_b128 v[188:191], v192 offset:20480
	v_max3_f32 v179, v179, v107, v75
	v_max3_f32 v179, v179, v108, v76
	v_max3_f32 v179, v179, v109, v77
	s_waitcnt lgkmcnt(0)
	v_mfma_f32_32x32x16_bf16 v[116:131], v[182:185], v[140:143], v[116:131]
	ds_read_b128 v[182:185], v193 offset:20480
	v_max3_f32 v179, v179, v110, v78
	v_max3_f32 v179, v179, v111, v79
	v_max3_f32 v179, v179, v112, v80
	v_mfma_f32_32x32x16_bf16 v[84:99], v[188:191], v[140:143], v[84:99]
	v_max3_f32 v179, v179, v113, v81
	v_max3_f32 v179, v179, v114, v82
	s_waitcnt lgkmcnt(0)
	v_mfma_f32_32x32x16_bf16 v[84:99], v[182:185], v[144:147], v[84:99]
	ds_read_b128 v[182:185], v193 offset:16384
	s_waitcnt lgkmcnt(0)
	v_mfma_f32_32x32x16_bf16 v[116:131], v[182:185], v[144:147], v[116:131]
	s_nop 8
	v_max_f32_e32 v187, v84, v84
	v_and_b32_e32 v184, 64, v198
	v_max3_f32 v183, v179, v115, v83
	v_xor_b32_e32 v179, 32, v198
	v_add_u32_e32 v184, 64, v184
	v_cmp_lt_i32_e32 vcc, v179, v184
	v_max_f32_e32 v182, v116, v116
	v_max_f32_e32 v182, v182, v187
	v_max3_f32 v182, v182, v117, v85
	v_cndmask_b32_e32 v179, v198, v179, vcc
	v_max3_f32 v182, v182, v118, v86
	v_lshlrev_b32_e32 v179, 2, v179
	v_max3_f32 v182, v182, v119, v87
	v_mov_b32_e32 v184, v183
	v_max3_f32 v182, v182, v120, v88
	v_max3_f32 v182, v182, v121, v89
	v_max3_f32 v182, v182, v122, v90
	v_max3_f32 v182, v182, v123, v91
	v_max3_f32 v182, v182, v124, v92
	v_max3_f32 v182, v182, v125, v93
	v_max3_f32 v182, v182, v126, v94
	v_max3_f32 v182, v182, v127, v95
	v_max3_f32 v182, v182, v128, v96
	v_max3_f32 v182, v182, v129, v97
	v_max3_f32 v182, v182, v130, v98
	v_max3_f32 v185, v182, v131, v99
	v_mov_b32_e32 v187, v185
	v_permlane32_swap_b32_e32 v184, v183
	s_nop 0
	v_permlane32_swap_b32_e32 v187, v185
	v_max_f32_e32 v182, v183, v184
	s_nop 0
	v_max_f32_e32 v183, v185, v187
	v_cndmask_b32_e64 v183, v186, v183, s[4:5]
	v_pk_add_f32 v[184:185], v[180:181], s[46:47] op_sel_hi:[1,0]
	s_nop 0
	v_cmp_gt_f32_e64 s[6:7], v182, v184
	v_cmp_gt_f32_e64 s[8:9], v183, v185
	s_or_b64 vcc, s[6:7], s[8:9]
	s_cbranch_vccz .LBB0_728
	v_cndmask_b32_e64 v183, v181, v183, s[8:9]
	v_cndmask_b32_e64 v182, v180, v182, s[6:7]
	v_pk_add_f32 v[180:181], v[180:181], v[182:183] neg_lo:[0,1] neg_hi:[0,1]
	s_nop 0
	v_mul_f32_e32 v180, 0x3e38aa3b, v180
	v_mul_f32_e32 v181, 0x3e38aa3b, v181
	v_exp_f32_e32 v181, v181
	v_exp_f32_e32 v180, v180
	v_cndmask_b32_e64 v181, 1.0, v181, s[8:9]
	v_cndmask_b32_e64 v180, 1.0, v180, s[6:7]
	v_pk_mul_f32 v[172:173], v[172:173], v[180:181]
	v_pk_mul_f32 v[66:67], v[66:67], v[180:181] op_sel_hi:[1,0]
	v_pk_mul_f32 v[64:65], v[64:65], v[180:181] op_sel_hi:[1,0]
	v_pk_mul_f32 v[62:63], v[62:63], v[180:181] op_sel_hi:[1,0]
	v_pk_mul_f32 v[60:61], v[60:61], v[180:181] op_sel_hi:[1,0]
	v_pk_mul_f32 v[58:59], v[58:59], v[180:181] op_sel_hi:[1,0]
	v_pk_mul_f32 v[56:57], v[56:57], v[180:181] op_sel_hi:[1,0]
	v_pk_mul_f32 v[54:55], v[54:55], v[180:181] op_sel_hi:[1,0]
	v_pk_mul_f32 v[52:53], v[52:53], v[180:181] op_sel_hi:[1,0]
	v_pk_mul_f32 v[18:19], v[18:19], v[180:181] op_sel_hi:[1,0]
	v_pk_mul_f32 v[16:17], v[16:17], v[180:181] op_sel_hi:[1,0]
	v_pk_mul_f32 v[14:15], v[14:15], v[180:181] op_sel_hi:[1,0]
	v_pk_mul_f32 v[12:13], v[12:13], v[180:181] op_sel_hi:[1,0]
	v_pk_mul_f32 v[10:11], v[10:11], v[180:181] op_sel_hi:[1,0]
	v_pk_mul_f32 v[8:9], v[8:9], v[180:181] op_sel_hi:[1,0]
	v_pk_mul_f32 v[6:7], v[6:7], v[180:181] op_sel_hi:[1,0]
	v_pk_mul_f32 v[4:5], v[4:5], v[180:181] op_sel_hi:[1,0]
	v_mov_b32_e32 v180, v181
	v_pk_mul_f32 v[50:51], v[50:51], v[180:181] op_sel_hi:[1,0]
	v_pk_mul_f32 v[48:49], v[48:49], v[180:181] op_sel_hi:[1,0]
	v_pk_mul_f32 v[46:47], v[46:47], v[180:181] op_sel_hi:[1,0]
	v_pk_mul_f32 v[44:45], v[44:45], v[180:181] op_sel_hi:[1,0]
	v_pk_mul_f32 v[42:43], v[42:43], v[180:181] op_sel_hi:[1,0]
	v_pk_mul_f32 v[40:41], v[40:41], v[180:181] op_sel_hi:[1,0]
	v_pk_mul_f32 v[38:39], v[38:39], v[180:181] op_sel_hi:[1,0]
	v_pk_mul_f32 v[36:37], v[36:37], v[180:181] op_sel_hi:[1,0]
	v_pk_mul_f32 v[34:35], v[34:35], v[180:181] op_sel_hi:[1,0]
	v_pk_mul_f32 v[32:33], v[32:33], v[180:181] op_sel_hi:[1,0]
	v_pk_mul_f32 v[30:31], v[30:31], v[180:181] op_sel_hi:[1,0]
	v_pk_mul_f32 v[28:29], v[28:29], v[180:181] op_sel_hi:[1,0]
	v_pk_mul_f32 v[26:27], v[26:27], v[180:181] op_sel_hi:[1,0]
	v_pk_mul_f32 v[24:25], v[24:25], v[180:181] op_sel_hi:[1,0]
	v_pk_mul_f32 v[22:23], v[22:23], v[180:181] op_sel_hi:[1,0]
	v_pk_mul_f32 v[20:21], v[20:21], v[180:181] op_sel_hi:[1,0]
	v_mov_b64_e32 v[180:181], v[182:183]
